# streaming (nt) cache policy on the read-once f32 K/V stream loads of the cross-attention sample unit
# baseline (speedup 1.0000x reference)
.LBB0_154:
	s_or_b64 exec, exec, s[6:7]
	v_mov_b32_e32 v0, s86
	s_waitcnt lgkmcnt(0)
	s_barrier
	ds_read_b32 v0, v0
	s_mov_b64 s[6:7], -1
	s_waitcnt lgkmcnt(0)
	v_cmp_lt_i32_e32 vcc, s58, v0
	v_readfirstlane_b32 s24, v0
	s_cbranch_vccnz .LBB0_151
	s_bitcmp0_b32 s24, 0
	s_cbranch_scc1 .LBB0_179
	s_andn2_b64 vcc, exec, s[12:13]
	s_cbranch_vccnz .LBB0_178
	s_ashr_i32 s0, s24, 3
	s_add_i32 s20, s0, s52
	s_mov_b32 s71, s69
	s_mov_b64 s[68:69], s[76:77]
	s_mov_b64 s[66:67], s[78:79]
	s_mov_b64 s[64:65], s[80:81]
	s_ashr_i32 s21, s20, 31
	v_readlane_b32 s72, v253, 42
	s_and_b32 s25, s24, -8
	s_lshl_b64 s[22:23], s[20:21], 20
	v_readlane_b32 s82, v253, 52
	v_readlane_b32 s83, v253, 53
	s_add_u32 s21, s82, s22
	s_addc_u32 s55, s83, s23
	s_lshl_b32 s0, s24, 7
	s_and_b32 s0, s0, 0x300
	s_mov_b64 s[6:7], s[94:95]
	v_mov_b32_e32 v216, v191
	s_lshl_b32 s20, s0, 2
	s_add_u32 s54, s21, s20
	v_lshlrev_b32_e32 v0, 5, v216
	v_ashrrev_i32_e32 v74, 3, v216
	v_add_u32_e32 v217, 0x200, v216
	s_addc_u32 s55, s55, 0
	v_and_b32_e32 v152, 0xe0, v0
	v_ashrrev_i32_e32 v75, 31, v74
	v_ashrrev_i32_e32 v76, 3, v217
	v_lshl_add_u64 v[0:1], s[54:55], 0, v[152:153]
	v_lshlrev_b64 v[2:3], 12, v[74:75]
	v_ashrrev_i32_e32 v77, 31, v76
	v_lshl_add_u64 v[32:33], v[0:1], 0, v[2:3]
	v_lshlrev_b64 v[2:3], 12, v[76:77]
	v_lshl_add_u64 v[34:35], v[0:1], 0, v[2:3]
	v_add_u32_e32 v2, 0x400, v216
	v_ashrrev_i32_e32 v78, 3, v2
	v_ashrrev_i32_e32 v79, 31, v78
	v_lshlrev_b64 v[2:3], 12, v[78:79]
	v_lshl_add_u64 v[36:37], v[0:1], 0, v[2:3]
	v_add_u32_e32 v2, 0x600, v216
	v_ashrrev_i32_e32 v80, 3, v2
	v_ashrrev_i32_e32 v81, 31, v80
	global_load_dwordx4 v[42:45], v[32:33], off offset:16 nt
	global_load_dwordx4 v[46:49], v[32:33], off nt
	global_load_dwordx4 v[50:53], v[34:35], off offset:16 nt
	global_load_dwordx4 v[54:57], v[34:35], off nt
	v_lshlrev_b64 v[2:3], 12, v[80:81]
	global_load_dwordx4 v[58:61], v[36:37], off offset:16 nt
	global_load_dwordx4 v[62:65], v[36:37], off nt
	v_lshl_add_u64 v[38:39], v[0:1], 0, v[2:3]
	global_load_dwordx4 v[66:69], v[38:39], off offset:16 nt
	global_load_dwordx4 v[70:73], v[38:39], off nt
	v_lshlrev_b32_e32 v41, 4, v216
	v_add_u32_e32 v40, s25, v97
	v_and_b32_e32 v41, 0x70, v41
	v_readlane_b32 s84, v253, 54
	v_add_u32_e32 v82, 0, v41
	v_ashrrev_i32_e32 v41, 31, v40
	v_readlane_b32 s85, v253, 55
	s_add_u32 s21, s84, s22
	v_lshlrev_b64 v[162:163], 11, v[40:41]
	s_addc_u32 s22, s85, s23
	s_movk_i32 s23, 0x90
	v_lshl_add_u64 v[40:41], s[6:7], 0, v[162:163]
	s_lshl_b32 s0, s0, 1
	v_mad_u64_u32 v[164:165], s[54:55], v74, s23, v[82:83]
	v_mad_u64_u32 v[166:167], s[54:55], v76, s23, v[82:83]
	v_mad_u64_u32 v[168:169], s[54:55], v78, s23, v[82:83]
	v_mad_u64_u32 v[170:171], s[54:55], v80, s23, v[82:83]
	v_lshl_add_u64 v[40:41], v[40:41], 0, s[0:1]
	v_lshlrev_b32_e32 v152, 1, v96
	global_load_dwordx4 v[0:3], v[32:33], off offset:272 nt
	global_load_dwordx4 v[20:23], v[32:33], off offset:256 nt
	global_load_dwordx4 v[4:7], v[34:35], off offset:272 nt
	global_load_dwordx4 v[24:27], v[34:35], off offset:256 nt
	global_load_dwordx4 v[8:11], v[36:37], off offset:272 nt
	global_load_dwordx4 v[28:31], v[36:37], off offset:256 nt
	global_load_dwordx4 v[12:15], v[38:39], off offset:272 nt
	global_load_dwordx4 v[16:19], v[38:39], off offset:256 nt
	v_lshl_add_u64 v[40:41], v[40:41], 0, v[152:153]
	s_mov_b64 s[54:55], 0x1b500000
	s_mov_b32 s23, 0x1b500000
	v_lshl_add_u64 v[172:173], v[40:41], 0, s[54:55]
	v_add_co_u32_e32 v40, vcc, s23, v40
	s_add_u32 s20, s21, s20
	s_nop 0
	v_addc_co_u32_e32 v41, vcc, 0, v41, vcc
	global_load_dwordx4 v[226:229], v[172:173], off
	global_load_dwordx4 v[230:233], v[172:173], off offset:64
	s_addc_u32 s21, s22, 0
	s_mov_b64 s[22:23], 0x1000
	v_readlane_b32 s73, v253, 43
	v_readlane_b32 s74, v253, 44
	v_readlane_b32 s75, v253, 45
	v_readlane_b32 s76, v253, 46
	v_readlane_b32 s77, v253, 47
	v_readlane_b32 s78, v253, 48
	v_readlane_b32 s79, v253, 49
	v_readlane_b32 s80, v253, 50
	v_readlane_b32 s81, v253, 51
	v_readlane_b32 s86, v253, 56
	v_readlane_b32 s87, v253, 57
	s_waitcnt vmcnt(10)
	v_cvt_pk_bf16_f32 v46, v46, v47
	v_cvt_pk_bf16_f32 v47, v48, v49
	v_cvt_pk_bf16_f32 v48, v42, v43
	v_cvt_pk_bf16_f32 v49, v44, v45
	v_cvt_pk_bf16_f32 v42, v54, v55
	v_cvt_pk_bf16_f32 v43, v56, v57
	v_cvt_pk_bf16_f32 v44, v50, v51
	v_cvt_pk_bf16_f32 v45, v52, v53
	ds_write_b128 v164, v[46:49]
	ds_write_b128 v166, v[42:45]
	v_cvt_pk_bf16_f32 v42, v62, v63
	v_cvt_pk_bf16_f32 v43, v64, v65
	v_cvt_pk_bf16_f32 v44, v58, v59
	v_cvt_pk_bf16_f32 v45, v60, v61
	ds_write_b128 v168, v[42:45]
	v_cvt_pk_bf16_f32 v42, v70, v71
	v_cvt_pk_bf16_f32 v43, v72, v73
	v_cvt_pk_bf16_f32 v44, v66, v67
	v_cvt_pk_bf16_f32 v45, v68, v69
	ds_write_b128 v170, v[42:45]
	global_load_dwordx4 v[234:237], v[172:173], off offset:128
	global_load_dwordx4 v[238:241], v[172:173], off offset:192
	global_load_dwordx4 v[88:91], v[32:33], off offset:528 nt
	global_load_dwordx4 v[92:95], v[32:33], off offset:512 nt
	global_load_dwordx4 v[72:75], v[34:35], off offset:528 nt
	global_load_dwordx4 v[80:83], v[34:35], off offset:512 nt
	global_load_dwordx4 v[64:67], v[36:37], off offset:528 nt
	global_load_dwordx4 v[68:71], v[36:37], off offset:512 nt
	global_load_dwordx4 v[76:79], v[38:39], off offset:528 nt
	global_load_dwordx4 v[84:87], v[38:39], off offset:512 nt
	s_waitcnt lgkmcnt(0)
	s_barrier
	s_waitcnt vmcnt(10)
	ds_read_b128 v[44:47], v193
	ds_read_b128 v[52:55], v193 offset:64
	ds_read_b128 v[48:51], v193 offset:2304
	v_cvt_pk_bf16_f32 v20, v20, v21
	v_cvt_pk_bf16_f32 v21, v22, v23
	v_cvt_pk_bf16_f32 v22, v0, v1
	v_cvt_pk_bf16_f32 v23, v2, v3
	v_cvt_pk_bf16_f32 v0, v24, v25
	v_cvt_pk_bf16_f32 v1, v26, v27
	v_cvt_pk_bf16_f32 v2, v4, v5
	v_cvt_pk_bf16_f32 v3, v6, v7
	s_waitcnt lgkmcnt(0)
	v_mfma_f32_16x16x32_bf16 v[44:47], v[44:47], v[226:229], 0
	v_mfma_f32_16x16x32_bf16 v[40:43], v[48:51], v[226:229], 0
	v_mfma_f32_16x16x32_bf16 v[218:221], v[52:55], v[230:233], v[44:47]
	s_nop 3
	ds_read_b128 v[44:47], v193 offset:2368
	s_waitcnt lgkmcnt(0)
	s_barrier
	ds_write_b128 v164, v[20:23]
	ds_write_b128 v166, v[0:3]
	v_cvt_pk_bf16_f32 v0, v28, v29
	v_cvt_pk_bf16_f32 v1, v30, v31
	v_cvt_pk_bf16_f32 v2, v8, v9
	v_cvt_pk_bf16_f32 v3, v10, v11
	ds_write_b128 v168, v[0:3]
	v_cvt_pk_bf16_f32 v0, v16, v17
	v_cvt_pk_bf16_f32 v1, v18, v19
	v_cvt_pk_bf16_f32 v2, v12, v13
	v_cvt_pk_bf16_f32 v3, v14, v15
	ds_write_b128 v170, v[0:3]
	v_mfma_f32_16x16x32_bf16 v[222:225], v[44:47], v[230:233], v[40:43]
	global_load_dwordx4 v[226:229], v[172:173], off offset:256
	global_load_dwordx4 v[230:233], v[172:173], off offset:320
	global_load_dwordx4 v[56:59], v[32:33], off offset:784 nt
	global_load_dwordx4 v[60:63], v[32:33], off offset:768 nt
	global_load_dwordx4 v[48:51], v[34:35], off offset:784 nt
	global_load_dwordx4 v[52:55], v[34:35], off offset:768 nt
	global_load_dwordx4 v[40:43], v[36:37], off offset:784 nt
	global_load_dwordx4 v[44:47], v[36:37], off offset:768 nt
	s_nop 0
	global_load_dwordx4 v[32:35], v[38:39], off offset:784 nt
	s_nop 0
	global_load_dwordx4 v[36:39], v[38:39], off offset:768 nt
	s_waitcnt lgkmcnt(0)
	s_barrier
	s_waitcnt vmcnt(0)
	ds_read_b128 v[4:7], v193
	ds_read_b128 v[12:15], v193 offset:64
	ds_read_b128 v[8:11], v193 offset:2304
	s_waitcnt lgkmcnt(0)
	v_mfma_f32_16x16x32_bf16 v[4:7], v[4:7], v[234:237], v[218:221]
	v_cvt_pk_bf16_f32 v60, v60, v61
	v_cvt_pk_bf16_f32 v61, v62, v63
	v_cvt_pk_bf16_f32 v62, v56, v57
	v_mfma_f32_16x16x32_bf16 v[0:3], v[8:11], v[234:237], v[222:225]
	v_cvt_pk_bf16_f32 v63, v58, v59
	v_cvt_pk_bf16_f32 v52, v52, v53
	v_cvt_pk_bf16_f32 v53, v54, v55
	v_cvt_pk_bf16_f32 v54, v48, v49
	v_cvt_pk_bf16_f32 v55, v50, v51
	v_cvt_pk_bf16_f32 v44, v44, v45
	v_cvt_pk_bf16_f32 v45, v46, v47
	v_cvt_pk_bf16_f32 v46, v40, v41
	v_cvt_pk_bf16_f32 v47, v42, v43
	v_cvt_pk_bf16_f32 v36, v36, v37
	v_cvt_pk_bf16_f32 v37, v38, v39
	v_cvt_pk_bf16_f32 v38, v32, v33
	s_waitcnt lgkmcnt(0)
	v_mfma_f32_16x16x32_bf16 v[218:221], v[12:15], v[238:241], v[4:7]
	s_nop 2
	ds_read_b128 v[4:7], v193 offset:2368
	s_waitcnt lgkmcnt(0)
	s_barrier
	v_mfma_f32_16x16x32_bf16 v[222:225], v[4:7], v[238:241], v[0:3]
	s_nop 2
	v_cvt_pk_bf16_f32 v0, v92, v93
	v_cvt_pk_bf16_f32 v1, v94, v95
	v_cvt_pk_bf16_f32 v2, v88, v89
	v_cvt_pk_bf16_f32 v3, v90, v91
	ds_write_b128 v164, v[0:3]
	v_cvt_pk_bf16_f32 v0, v80, v81
	v_cvt_pk_bf16_f32 v1, v82, v83
	v_cvt_pk_bf16_f32 v2, v72, v73
	v_cvt_pk_bf16_f32 v3, v74, v75
	ds_write_b128 v166, v[0:3]
	v_cvt_pk_bf16_f32 v0, v68, v69
	v_cvt_pk_bf16_f32 v1, v70, v71
	v_cvt_pk_bf16_f32 v2, v64, v65
	v_cvt_pk_bf16_f32 v3, v66, v67
	ds_write_b128 v168, v[0:3]
	v_cvt_pk_bf16_f32 v0, v84, v85
	v_cvt_pk_bf16_f32 v1, v86, v87
	v_cvt_pk_bf16_f32 v2, v76, v77
	v_cvt_pk_bf16_f32 v3, v78, v79
	ds_write_b128 v170, v[0:3]
	v_lshlrev_b32_e32 v0, 11, v216
	v_lshlrev_b32_e32 v2, 3, v216
	v_and_b32_e32 v152, 0xfe000, v0
	v_and_b32_e32 v82, 24, v2
	v_lshl_add_u64 v[0:1], s[20:21], 0, v[152:153]
	v_ashrrev_i32_e32 v83, 31, v82
	v_lshl_add_u64 v[72:73], v[82:83], 2, v[0:1]
	s_movk_i32 s20, 0x1000
	v_add_co_u32_e32 v76, vcc, s20, v72
	v_lshl_add_u64 v[2:3], v[72:73], 0, s[22:23]
	s_nop 0
	v_addc_co_u32_e32 v77, vcc, 0, v73, vcc
	global_load_dwordx4 v[234:237], v[172:173], off offset:384
	global_load_dwordx4 v[238:241], v[172:173], off offset:448
	global_load_dwordx4 v[16:19], v[72:73], off offset:16 nt
	global_load_dwordx4 v[20:23], v[72:73], off nt
	global_load_dwordx4 v[28:31], v[76:77], off nt
	global_load_dwordx4 v[24:27], v[2:3], off offset:16 nt
	v_lshlrev_b32_e32 v2, 3, v216
	v_and_or_b32 v80, v2, 24, 32
	v_ashrrev_i32_e32 v81, 31, v80
	v_lshl_add_u64 v[74:75], v[80:81], 2, v[0:1]
	v_add_co_u32_e32 v78, vcc, s20, v74
	v_lshl_add_u64 v[8:9], v[74:75], 0, s[22:23]
	s_nop 0
	v_addc_co_u32_e32 v79, vcc, 0, v75, vcc
	global_load_dwordx4 v[0:3], v[74:75], off offset:16 nt
	global_load_dwordx4 v[4:7], v[74:75], off nt
	global_load_dwordx4 v[12:15], v[78:79], off nt
	s_nop 0
	global_load_dwordx4 v[8:11], v[8:9], off offset:16 nt
	s_waitcnt lgkmcnt(0)
	s_barrier
	s_waitcnt vmcnt(10)
	ds_read_b128 v[68:71], v193
	ds_read_b128 v[88:91], v193 offset:64
	ds_read_b128 v[84:87], v193 offset:2304
	s_waitcnt lgkmcnt(0)
	v_mfma_f32_16x16x32_bf16 v[68:71], v[68:71], v[226:229], v[218:221]
	v_cvt_pk_bf16_f32 v39, v34, v35
	s_mov_b64 s[20:21], 0x1100
	v_lshl_add_u64 v[32:33], v[72:73], 0, s[20:21]
	v_mfma_f32_16x16x32_bf16 v[64:67], v[84:87], v[226:229], v[222:225]
	v_mfma_f32_16x16x32_bf16 v[68:71], v[88:91], v[230:233], v[68:71]
	ds_read_b128 v[88:91], v193 offset:2368
	s_waitcnt lgkmcnt(0)
	s_barrier
	ds_write_b128 v164, v[60:63]
	ds_write_b128 v166, v[52:55]
	ds_write_b128 v168, v[44:47]
	ds_write_b128 v170, v[36:39]
	v_lshl_add_u64 v[44:45], v[74:75], 0, s[20:21]
	v_mfma_f32_16x16x32_bf16 v[64:67], v[88:91], v[230:233], v[64:67]
	global_load_dwordx4 v[48:51], v[72:73], off offset:272 nt
	global_load_dwordx4 v[60:63], v[72:73], off offset:256 nt
	global_load_dwordx4 v[56:59], v[76:77], off offset:256 nt
	global_load_dwordx4 v[52:55], v[32:33], off offset:16 nt
	s_nop 0
	global_load_dwordx4 v[32:35], v[74:75], off offset:272 nt
	global_load_dwordx4 v[36:39], v[74:75], off offset:256 nt
	global_load_dwordx4 v[40:43], v[78:79], off offset:256 nt
	s_nop 0
	global_load_dwordx4 v[44:47], v[44:45], off offset:16 nt
	s_waitcnt lgkmcnt(0)
	s_barrier
	s_waitcnt vmcnt(8)
	ds_read_b128 v[88:91], v193
	s_waitcnt lgkmcnt(0)
	v_mfma_f32_16x16x32_bf16 v[68:71], v[88:91], v[234:237], v[68:71]
	ds_read_b128 v[88:91], v193 offset:2304
	s_waitcnt lgkmcnt(0)
	v_mfma_f32_16x16x32_bf16 v[64:67], v[88:91], v[234:237], v[64:67]
	ds_read_b128 v[88:91], v193 offset:64
	s_waitcnt lgkmcnt(0)
	v_mfma_f32_16x16x32_bf16 v[68:71], v[88:91], v[238:241], v[68:71]
	ds_read_b128 v[88:91], v193 offset:2368
	s_nop 6
	v_max_f32_e32 v81, v69, v69
	s_waitcnt lgkmcnt(0)
	v_mfma_f32_16x16x32_bf16 v[64:67], v[88:91], v[238:241], v[64:67]
	v_max_f32_e32 v83, v68, v68
	v_max_f32_e32 v81, v83, v81
	v_max_f32_e32 v83, v71, v71
	v_max_f32_e32 v84, v70, v70
	v_max_f32_e32 v83, v84, v83
	s_nop 2
	v_max_f32_e32 v84, v67, v67
	v_max_f32_e32 v85, v66, v66
	v_max_f32_e32 v84, v85, v84
	v_max3_f32 v84, v64, v65, v84
	v_max3_f32 v83, v81, v83, v84
	v_and_b32_e32 v84, 64, v188
	v_xor_b32_e32 v81, 16, v188
	v_add_u32_e32 v84, 64, v84
	v_cmp_lt_i32_e32 vcc, v81, v84
	s_nop 1
	v_cndmask_b32_e32 v81, v188, v81, vcc
	v_lshlrev_b32_e32 v81, 2, v81
	ds_bpermute_b32 v85, v81, v83
	s_waitcnt lgkmcnt(0)
	v_max_f32_e32 v85, v85, v85
	v_max_f32_e32 v85, v83, v85
	v_xor_b32_e32 v83, 32, v188
	v_cmp_lt_i32_e32 vcc, v83, v84
	s_nop 1
	v_cndmask_b32_e32 v83, v188, v83, vcc
	v_lshlrev_b32_e32 v83, 2, v83
	ds_bpermute_b32 v84, v83, v85
	s_waitcnt lgkmcnt(0)
	v_max_f32_e32 v84, v84, v84
	v_max_f32_e32 v84, v85, v84
	s_and_saveexec_b64 s[20:21], s[8:9]
	ds_write_b32 v212, v84 offset:45312
	s_or_b64 exec, exec, s[20:21]
	v_add_u32_e32 v88, 0xb000, v174
	s_waitcnt lgkmcnt(0)
	s_barrier
	ds_read2_b32 v[86:87], v88 offset0:64 offset1:80
	s_waitcnt lgkmcnt(0)
	v_max3_f32 v86, v84, v86, v87
	ds_read2_b32 v[84:85], v88 offset0:96 offset1:112
	s_waitcnt lgkmcnt(0)
	v_max3_f32 v86, v86, v84, v85
	ds_read2_b32 v[84:85], v88 offset0:128 offset1:144
	s_waitcnt lgkmcnt(0)
	v_max3_f32 v86, v86, v84, v85
	ds_read2_b32 v[84:85], v88 offset0:160 offset1:176
	s_waitcnt lgkmcnt(0)
	v_max3_f32 v84, v86, v84, v85
	v_sub_f32_e32 v68, v68, v84
	v_mul_f32_e32 v68, 0x3fb8aa3b, v68
	v_sub_f32_e32 v69, v69, v84
	v_exp_f32_e32 v68, v68
	v_mul_f32_e32 v69, 0x3fb8aa3b, v69
	v_sub_f32_e32 v70, v70, v84
	v_exp_f32_e32 v69, v69
	v_mul_f32_e32 v70, 0x3fb8aa3b, v70
	v_sub_f32_e32 v71, v71, v84
	v_exp_f32_e32 v70, v70
	v_mul_f32_e32 v71, 0x3fb8aa3b, v71
	v_sub_f32_e32 v64, v64, v84
	v_exp_f32_e32 v71, v71
	v_mul_f32_e32 v64, 0x3fb8aa3b, v64
	v_sub_f32_e32 v65, v65, v84
	v_add_f32_e32 v85, 0, v68
	v_exp_f32_e32 v64, v64
	v_mul_f32_e32 v65, 0x3fb8aa3b, v65
	v_sub_f32_e32 v66, v66, v84
	v_add_f32_e32 v85, v69, v85
	v_exp_f32_e32 v65, v65
	v_mul_f32_e32 v66, 0x3fb8aa3b, v66
	v_sub_f32_e32 v67, v67, v84
	v_add_f32_e32 v85, v70, v85
	v_exp_f32_e32 v66, v66
	v_mul_f32_e32 v67, 0x3fb8aa3b, v67
	v_add_f32_e32 v85, v71, v85
	v_exp_f32_e32 v67, v67
	v_cvt_pk_bf16_f32 v68, v68, v69
	v_cvt_pk_bf16_f32 v69, v70, v71
	v_add_f32_e32 v70, v64, v85
	v_add_f32_e32 v70, v65, v70
	v_add_f32_e32 v70, v66, v70
	v_add_f32_e32 v70, v67, v70
	v_cvt_pk_bf16_f32 v64, v64, v65
	v_cvt_pk_bf16_f32 v65, v66, v67
	ds_write2_b64 v213, v[68:69], v[64:65] offset1:4
	ds_bpermute_b32 v64, v81, v70
	s_waitcnt lgkmcnt(0)
	v_add_f32_e32 v64, v70, v64
	ds_bpermute_b32 v65, v83, v64
	s_and_saveexec_b64 s[20:21], s[8:9]
	s_cbranch_execz .LBB0_161
	s_waitcnt lgkmcnt(0)
	v_add_f32_e32 v64, v64, v65
	ds_write_b32 v212, v64 offset:45824
.LBB0_161:
	s_or_b64 exec, exec, s[20:21]
	v_mov_b32_e32 v64, v216
	s_add_u32 s20, s6, 0x17100000
	v_and_b32_e32 v64, 0x1fc, v64
	s_movk_i32 s6, 0x210
	v_add_u32_e32 v64, 0, v64
	v_cvt_pk_bf16_f32 v20, v20, v21
	v_cvt_pk_bf16_f32 v21, v22, v23
	v_cvt_pk_bf16_f32 v22, v24, v25
	v_mul_lo_u32 v24, v82, s6
	v_cvt_pk_bf16_f32 v16, v16, v17
	v_cvt_pk_bf16_f32 v17, v18, v19
	v_cvt_pk_bf16_f32 v18, v28, v29
	v_add_u32_e32 v69, v64, v24
	v_and_b32_e32 v24, 0xffff, v20
	v_lshrrev_b32_e32 v20, 16, v20
	v_lshl_or_b32 v24, v18, 16, v24
	v_and_or_b32 v18, v18, s59, v20
	v_cvt_pk_bf16_f32 v19, v30, v31
	ds_write2_b32 v69, v24, v18 offset1:132
	v_and_b32_e32 v18, 0xffff, v21
	v_lshrrev_b32_e32 v20, 16, v21
	v_lshl_or_b32 v18, v19, 16, v18
	v_and_or_b32 v19, v19, s59, v20
	v_add_u32_e32 v70, 0x400, v69
	ds_write2_b32 v70, v18, v19 offset0:8 offset1:140
	v_and_b32_e32 v18, 0xffff, v16
	v_lshrrev_b32_e32 v16, 16, v16
	v_lshl_or_b32 v18, v22, 16, v18
	v_and_or_b32 v16, v22, s59, v16
	v_add_u32_e32 v81, 0x800, v69
	v_cvt_pk_bf16_f32 v4, v4, v5
	v_cvt_pk_bf16_f32 v5, v6, v7
	v_cvt_pk_bf16_f32 v6, v8, v9
	v_mul_lo_u32 v8, v80, s6
	v_cvt_pk_bf16_f32 v23, v26, v27
	ds_write2_b32 v81, v18, v16 offset0:16 offset1:148
	v_and_b32_e32 v16, 0xffff, v17
	v_lshrrev_b32_e32 v17, 16, v17
	v_cvt_pk_bf16_f32 v0, v0, v1
	v_cvt_pk_bf16_f32 v1, v2, v3
	v_cvt_pk_bf16_f32 v2, v12, v13
	v_add_u32_e32 v71, v64, v8
	v_and_b32_e32 v8, 0xffff, v4
	v_lshrrev_b32_e32 v4, 16, v4
	v_lshl_or_b32 v16, v23, 16, v16
	v_and_or_b32 v17, v23, s59, v17
	v_add_u32_e32 v82, 0xc00, v69
	v_lshl_or_b32 v8, v2, 16, v8
	v_and_or_b32 v2, v2, s59, v4
	ds_write2_b32 v82, v16, v17 offset0:24 offset1:156
	v_cvt_pk_bf16_f32 v3, v14, v15
	ds_write2_b32 v71, v8, v2 offset1:132
	v_and_b32_e32 v2, 0xffff, v5
	v_lshrrev_b32_e32 v4, 16, v5
	v_lshl_or_b32 v2, v3, 16, v2
	v_and_or_b32 v3, v3, s59, v4
	v_add_u32_e32 v80, 0x400, v71
	ds_write2_b32 v80, v2, v3 offset0:8 offset1:140
	v_and_b32_e32 v2, 0xffff, v0
	v_lshrrev_b32_e32 v0, 16, v0
	v_lshl_or_b32 v2, v6, 16, v2
	v_and_or_b32 v0, v6, s59, v0
	v_add_u32_e32 v83, 0x800, v71
	v_cvt_pk_bf16_f32 v7, v10, v11
	ds_write2_b32 v83, v2, v0 offset0:16 offset1:148
	v_and_b32_e32 v0, 0xffff, v1
	v_lshrrev_b32_e32 v1, 16, v1
	s_addc_u32 s21, s7, 0
	v_lshl_or_b32 v0, v7, 16, v0
	v_and_or_b32 v1, v7, s59, v1
	v_add_u32_e32 v84, 0xc00, v71
	s_mov_b64 s[6:7], 0x1200
	ds_write2_b32 v84, v0, v1 offset0:24 offset1:156
	v_lshl_add_u64 v[0:1], v[72:73], 0, s[6:7]
	global_load_dwordx4 v[16:19], v[72:73], off offset:528 nt
	global_load_dwordx4 v[28:31], v[72:73], off offset:512 nt
	global_load_dwordx4 v[24:27], v[76:77], off offset:512 nt
	global_load_dwordx4 v[20:23], v[0:1], off offset:16 nt
	s_nop 0
	global_load_dwordx4 v[0:3], v[74:75], off offset:528 nt
	global_load_dwordx4 v[4:7], v[74:75], off offset:512 nt
	v_lshl_add_u64 v[12:13], v[74:75], 0, s[6:7]
	global_load_dwordx4 v[8:11], v[78:79], off offset:512 nt
	s_nop 0
	global_load_dwordx4 v[12:15], v[12:13], off offset:16 nt
	v_add_u32_e32 v66, 0xb000, v194
	s_waitcnt lgkmcnt(0)
	s_barrier
	ds_read2_b32 v[64:65], v66 offset0:192 offset1:208
	v_readlane_b32 s84, v254, 51
	v_readlane_b32 s83, v254, 49
	v_readlane_b32 s86, v254, 50
	s_mov_b32 s87, 0xf800000
	s_waitcnt lgkmcnt(0)
	v_add_f32_e32 v64, 0, v64
	v_add_f32_e32 v67, v64, v65
	ds_read2_b32 v[64:65], v66 offset0:224 offset1:240
	v_readlane_b32 s85, v254, 52
	v_readlane_b32 s72, v254, 57
	s_mov_b64 s[80:81], s[64:65]
	s_mov_b64 s[78:79], s[66:67]
	s_waitcnt lgkmcnt(0)
	v_add_f32_e32 v64, v67, v64
	v_add_u32_e32 v67, 0xb400, v194
	v_add_f32_e32 v66, v64, v65
	ds_read2_b32 v[64:65], v67 offset1:16
	s_mov_b64 s[76:77], s[68:69]
	s_mov_b32 s69, s71
	s_waitcnt lgkmcnt(0)
	v_add_f32_e32 v64, v66, v64
	v_add_f32_e32 v66, v64, v65
	ds_read2_b32 v[64:65], v67 offset0:32 offset1:48
	s_waitcnt lgkmcnt(0)
	v_add_f32_e32 v64, v66, v64
	v_add_f32_e32 v64, v64, v65
	v_div_scale_f32 v65, s[6:7], v64, v64, 1.0
	v_rcp_f32_e32 v66, v65
	s_nop 0
	v_fma_f32 v67, -v65, v66, 1.0
	v_fmac_f32_e32 v66, v67, v66
	v_div_scale_f32 v67, vcc, 1.0, v64, 1.0
	v_mul_f32_e32 v68, v67, v66
	v_fma_f32 v78, -v65, v68, v67
	v_fmac_f32_e32 v68, v78, v66
	v_fma_f32 v65, -v65, v68, v67
	v_div_fmas_f32 v65, v65, v66, v68
	v_div_fixup_f32 v68, v65, v64, 1.0
	v_cndmask_b32_e64 v64, 0, 1, s[14:15]
	v_cmp_ne_u32_e64 s[6:7], 1, v64
	s_andn2_b64 vcc, exec, s[14:15]
	v_add_u32_e32 v78, v175, v99
	s_cbranch_vccnz .LBB0_165
	ds_read_b128 v[64:67], v214
	ds_read_b128 v[86:89], v78 offset:36864
	s_waitcnt lgkmcnt(0)
	v_mfma_f32_16x16x32_bf16 v[64:67], v[64:67], v[86:89], 0
	ds_read_b128 v[86:89], v214 offset:64
	ds_read_b128 v[90:93], v78 offset:36928
	s_waitcnt lgkmcnt(0)
	v_mfma_f32_16x16x32_bf16 v[64:67], v[86:89], v[90:93], v[64:67]
	ds_read_b128 v[86:89], v214 offset:128
	ds_read_b128 v[90:93], v78 offset:36992
	s_waitcnt lgkmcnt(0)
	v_mfma_f32_16x16x32_bf16 v[64:67], v[86:89], v[90:93], v[64:67]
	ds_read_b128 v[86:89], v214 offset:192
	ds_read_b128 v[90:93], v78 offset:37056
	s_waitcnt lgkmcnt(0)
	v_mfma_f32_16x16x32_bf16 v[64:67], v[86:89], v[90:93], v[64:67]
	ds_read_b128 v[86:89], v214 offset:256
	ds_read_b128 v[90:93], v78 offset:37120
	s_waitcnt lgkmcnt(0)
	v_mfma_f32_16x16x32_bf16 v[64:67], v[86:89], v[90:93], v[64:67]
	ds_read_b128 v[86:89], v214 offset:320
	ds_read_b128 v[90:93], v78 offset:37184
	s_waitcnt lgkmcnt(0)
	v_mfma_f32_16x16x32_bf16 v[64:67], v[86:89], v[90:93], v[64:67]
	ds_read_b128 v[86:89], v214 offset:384
	ds_read_b128 v[90:93], v78 offset:37248
	s_waitcnt lgkmcnt(0)
	v_mfma_f32_16x16x32_bf16 v[64:67], v[86:89], v[90:93], v[64:67]
	ds_read_b128 v[86:89], v214 offset:448
	ds_read_b128 v[90:93], v78 offset:37312
	s_waitcnt lgkmcnt(0)
	v_mfma_f32_16x16x32_bf16 v[64:67], v[86:89], v[90:93], v[64:67]
	s_and_saveexec_b64 s[22:23], s[4:5]
	s_cbranch_execz .LBB0_164
	s_nop 5
	v_pk_mul_f32 v[64:65], v[68:69], v[64:65] op_sel_hi:[0,1]
	v_pk_mul_f32 v[66:67], v[68:69], v[66:67] op_sel_hi:[0,1]
	v_cvt_pk_bf16_f32 v64, v64, v65
	v_cvt_pk_bf16_f32 v65, v66, v67
	v_lshl_add_u64 v[66:67], s[20:21], 0, v[162:163]
	v_lshl_add_u64 v[66:67], v[66:67], 0, s[0:1]
	v_lshl_add_u64 v[66:67], s[16:17], 1, v[66:67]
	v_lshlrev_b32_e32 v152, 1, v98
	v_lshl_add_u64 v[66:67], v[66:67], 0, v[152:153]
	flat_store_dwordx2 v[66:67], v[64:65]

.LBB0_165:
	s_waitcnt vmcnt(8)
	v_cvt_pk_bf16_f32 v60, v60, v61
	v_cvt_pk_bf16_f32 v48, v48, v49
	v_cvt_pk_bf16_f32 v49, v50, v51
	v_cvt_pk_bf16_f32 v50, v56, v57
	v_cvt_pk_bf16_f32 v52, v52, v53
	v_cvt_pk_bf16_f32 v53, v54, v55
	v_and_b32_e32 v54, 0xffff, v60
	v_lshrrev_b32_e32 v55, 16, v60
	v_cvt_pk_bf16_f32 v61, v62, v63
	v_lshl_or_b32 v54, v50, 16, v54
	v_and_or_b32 v50, v50, s59, v55
	s_waitcnt lgkmcnt(0)
	s_barrier
	v_cvt_pk_bf16_f32 v51, v58, v59
	ds_write2_b32 v69, v54, v50 offset1:132
	v_and_b32_e32 v50, 0xffff, v61
	v_lshrrev_b32_e32 v54, 16, v61
	v_lshl_or_b32 v50, v51, 16, v50
	v_and_or_b32 v51, v51, s59, v54
	ds_write2_b32 v70, v50, v51 offset0:8 offset1:140
	v_and_b32_e32 v50, 0xffff, v48
	v_lshrrev_b32_e32 v48, 16, v48
	v_lshl_or_b32 v50, v52, 16, v50
	v_and_or_b32 v48, v52, s59, v48
	v_cvt_pk_bf16_f32 v36, v36, v37
	ds_write2_b32 v81, v50, v48 offset0:16 offset1:148
	v_and_b32_e32 v48, 0xffff, v49
	v_lshrrev_b32_e32 v49, 16, v49
	v_cvt_pk_bf16_f32 v32, v32, v33
	v_cvt_pk_bf16_f32 v33, v34, v35
	v_cvt_pk_bf16_f32 v34, v40, v41
	v_and_b32_e32 v40, 0xffff, v36
	v_lshrrev_b32_e32 v36, 16, v36
	v_lshl_or_b32 v48, v53, 16, v48
	v_and_or_b32 v49, v53, s59, v49
	v_cvt_pk_bf16_f32 v37, v38, v39
	v_lshl_or_b32 v40, v34, 16, v40
	v_and_or_b32 v34, v34, s59, v36
	ds_write2_b32 v82, v48, v49 offset0:24 offset1:156
	v_cvt_pk_bf16_f32 v35, v42, v43
	ds_write2_b32 v71, v40, v34 offset1:132
	v_and_b32_e32 v34, 0xffff, v37
	v_lshrrev_b32_e32 v36, 16, v37
	v_lshl_or_b32 v34, v35, 16, v34
	v_and_or_b32 v35, v35, s59, v36
	v_cvt_pk_bf16_f32 v38, v44, v45
	ds_write2_b32 v80, v34, v35 offset0:8 offset1:140
	v_and_b32_e32 v34, 0xffff, v32
	v_lshrrev_b32_e32 v32, 16, v32
	v_lshl_or_b32 v34, v38, 16, v34
	v_and_or_b32 v32, v38, s59, v32
	v_cvt_pk_bf16_f32 v39, v46, v47
	ds_write2_b32 v83, v34, v32 offset0:16 offset1:148
	v_and_b32_e32 v32, 0xffff, v33
	v_lshrrev_b32_e32 v33, 16, v33
	v_lshl_or_b32 v32, v39, 16, v32
	v_and_or_b32 v33, v39, s59, v33
	s_mov_b64 s[22:23], 0x1300
	ds_write2_b32 v84, v32, v33 offset0:24 offset1:156
	v_lshl_add_u64 v[32:33], v[72:73], 0, s[22:23]
	global_load_dwordx4 v[48:51], v[72:73], off offset:784 nt
	global_load_dwordx4 v[60:63], v[72:73], off offset:768 nt
	global_load_dwordx4 v[56:59], v[76:77], off offset:768 nt
	global_load_dwordx4 v[52:55], v[32:33], off offset:16 nt
	s_nop 0
	global_load_dwordx4 v[32:35], v[74:75], off offset:784 nt
	global_load_dwordx4 v[36:39], v[74:75], off offset:768 nt
	v_add_co_u32_e32 v42, vcc, 0x1000, v74
	v_lshl_add_u64 v[40:41], v[74:75], 0, s[22:23]
	s_nop 0
	v_addc_co_u32_e32 v43, vcc, 0, v75, vcc
	global_load_dwordx4 v[44:47], v[42:43], off offset:768 nt
	s_nop 0
	global_load_dwordx4 v[40:43], v[40:41], off offset:16 nt
	s_and_b64 vcc, exec, s[6:7]
	s_waitcnt lgkmcnt(0)
	s_barrier
	s_cbranch_vccnz .LBB0_169
	ds_read_b128 v[64:67], v214
	ds_read_b128 v[72:75], v78 offset:36864
	s_waitcnt lgkmcnt(0)
	v_mfma_f32_16x16x32_bf16 v[64:67], v[64:67], v[72:75], 0
	ds_read_b128 v[72:75], v214 offset:64
	ds_read_b128 v[86:89], v78 offset:36928
	s_waitcnt lgkmcnt(0)
	v_mfma_f32_16x16x32_bf16 v[64:67], v[72:75], v[86:89], v[64:67]
	ds_read_b128 v[72:75], v214 offset:128
	ds_read_b128 v[86:89], v78 offset:36992
	s_waitcnt lgkmcnt(0)
	v_mfma_f32_16x16x32_bf16 v[64:67], v[72:75], v[86:89], v[64:67]
	ds_read_b128 v[72:75], v214 offset:192
	ds_read_b128 v[86:89], v78 offset:37056
	s_waitcnt lgkmcnt(0)
	v_mfma_f32_16x16x32_bf16 v[64:67], v[72:75], v[86:89], v[64:67]
	ds_read_b128 v[72:75], v214 offset:256
	ds_read_b128 v[86:89], v78 offset:37120
	s_waitcnt lgkmcnt(0)
	v_mfma_f32_16x16x32_bf16 v[64:67], v[72:75], v[86:89], v[64:67]
	ds_read_b128 v[72:75], v214 offset:320
	ds_read_b128 v[86:89], v78 offset:37184
	s_waitcnt lgkmcnt(0)
	v_mfma_f32_16x16x32_bf16 v[64:67], v[72:75], v[86:89], v[64:67]
	ds_read_b128 v[72:75], v214 offset:384
	ds_read_b128 v[86:89], v78 offset:37248
	s_waitcnt lgkmcnt(0)
	v_mfma_f32_16x16x32_bf16 v[64:67], v[72:75], v[86:89], v[64:67]
	ds_read_b128 v[72:75], v214 offset:448
	ds_read_b128 v[86:89], v78 offset:37312
	s_waitcnt lgkmcnt(0)
	v_mfma_f32_16x16x32_bf16 v[64:67], v[72:75], v[86:89], v[64:67]
	s_and_saveexec_b64 s[22:23], s[4:5]
	s_cbranch_execz .LBB0_168
	s_nop 5
	v_pk_mul_f32 v[64:65], v[68:69], v[64:65] op_sel_hi:[0,1]
	v_pk_mul_f32 v[66:67], v[68:69], v[66:67] op_sel_hi:[0,1]
	v_cvt_pk_bf16_f32 v64, v64, v65
	v_cvt_pk_bf16_f32 v65, v66, v67
	v_lshl_add_u64 v[66:67], s[20:21], 0, v[162:163]
	v_lshl_add_u64 v[66:67], v[66:67], 0, s[0:1]
	v_lshl_add_u64 v[66:67], s[16:17], 1, v[66:67]
	v_lshlrev_b32_e32 v152, 1, v98
	v_lshl_add_u64 v[66:67], v[66:67], 0, v[152:153]
	flat_store_dwordx2 v[66:67], v[64:65] offset:128
